# attention unit prologues de-serialised: GQA first K/V tile loads issued with the Q loads; MLA tile-1 loads issued with tile 0 (spare staging registers) instead of after its LDS write
# baseline (speedup 1.0000x reference)
; template <int DQK, int DV, bool BIAS> ...
;     ...
; #pragma unroll
;     for (int ks = 0; ks < NKS; ++ks) qf[ks] = ks < 4 ? *(const bf16x8*)(Qw + (size_t)r32 * ldq + ks * 16 + hi * 8) : *(const bf16x8*)(Q2w + (size_t)r32 * ldq2 + (ks - 4) * 16 + hi * 8);
; #pragma unroll
;     for (int ks = 0; ks < 4; ++ks) qf[ks] = scale_frag(qf[ks], cs);
;     ...
;     const bf16_t* kptr = Kg + (size_t)(tid >> 3) * ldk + (tid & 7) * 8;
;     const bf16_t* k2ptr = (DQK == 96) ? K2g + (size_t)(tid >> 2) * ldk2 + (tid & 3) * 8 : nullptr;
;     ...
;     u32x4 pw[4];
; #pragma unroll
;     for (int j = 0; j < TPB; ++j) { ATT_LOAD(j, j); ATT_STORE(j, j); }
; #pragma unroll
;     for (int j = 0; j < TPB; ++j) ATT_LOAD(TPB + j, j);
.LBB0_600:
	s_xor_b64 s[8:9], s[10:11], -1
	s_add_i32 s10, s20, s33
	s_ashr_i32 s18, s10, 7
	s_ashr_i32 s19, s18, 31
	s_lshl_b64 s[10:11], s[18:19], 12
	s_add_u32 s10, s10, s27
	s_addc_u32 s11, s11, s48
	s_mulk_i32 s11, 0x1940
	s_mul_hi_u32 s19, s10, 0x1940
	v_mov_b32_e32 v34, v1
	s_add_i32 s19, s19, s11
	s_mulk_i32 s10, 0x1940
	s_add_u32 s10, s35, s10
	v_and_b32_e32 v35, 31, v34
	v_mul_u32_u24_e32 v2, 0xca0, v35
	s_addc_u32 s11, s36, s19
	v_bfe_u32 v36, v34, 5, 1
	v_lshlrev_b32_e32 v130, 1, v2
	v_lshl_add_u64 v[2:3], s[10:11], 0, v[130:131]
	v_lshlrev_b32_e32 v130, 4, v36
	v_lshl_add_u64 v[18:19], v[2:3], 0, v[130:131]
	global_load_dwordx4 v[2:5], v[18:19], off offset:3072
	global_load_dwordx4 v[6:9], v[18:19], off offset:3104
	global_load_dwordx4 v[10:13], v[18:19], off offset:3136
	global_load_dwordx4 v[14:17], v[18:19], off offset:3168
	s_mul_i32 s20, s18, 0x1940000
	s_mul_hi_i32 s19, s18, 0x1940000
	s_add_u32 s20, s16, s20
	s_addc_u32 s19, s17, s19
	s_add_u32 s20, s20, s38
	s_addc_u32 s21, s19, 0
	s_add_u32 s22, s20, 0x1000
	s_addc_u32 s23, s21, 0
	v_lshlrev_b32_e32 v36, 8, v36
	v_mad_u32_u24 v35, v35, s39, 0
	v_add_u32_e32 v130, v35, v130
	v_mov_b32_e32 v144, 0
	v_mov_b32_e32 v143, 0
	v_mov_b32_e32 v50, 0
	v_mov_b32_e32 v51, v131
	v_mov_b32_e32 v52, v131
	v_mov_b32_e32 v53, v131
	v_mov_b32_e32 v54, v131
	v_mov_b32_e32 v55, v131
	v_mov_b32_e32 v56, v131
	v_mov_b32_e32 v57, v131
	v_mov_b32_e32 v58, v131
	v_mov_b32_e32 v59, v131
	v_mov_b32_e32 v60, v131
	v_mov_b32_e32 v61, v131
	v_mov_b32_e32 v62, v131
	v_mov_b32_e32 v63, v131
	v_mov_b32_e32 v64, v131
	v_mov_b32_e32 v65, v131
	v_ashrrev_i32_e32 v192, 3, v34
	v_lshlrev_b32_e32 v193, 4, v34
	v_mov_b64_e32 v[194:195], s[22:23]
	v_mad_i64_i32 v[194:195], s[98:99], v192, s37, v[194:195]
	v_and_b32_e32 v196, 0x70, v193
	v_mov_b32_e32 v197, 0
	v_lshl_add_u64 v[198:199], v[194:195], 0, v[196:197]
	v_and_b32_e32 v194, 0xffffffe0, v192
	v_ashrrev_i32_e32 v195, 31, v194
	v_lshlrev_b64 v[200:201], 1, v[194:195]
	v_lshlrev_b32_e32 v202, 3, v34
	v_and_b32_e32 v202, 24, v202
	v_bfe_u32 v203, v34, 2, 6
	v_lshl_add_u64 v[194:195], s[20:21], 0, v[200:201]
	v_lshlrev_b32_e32 v204, 1, v202
	v_mov_b32_e32 v205, 0
	v_lshl_add_u64 v[194:195], v[194:195], 0, v[204:205]
	v_mul_u32_u24_e32 v204, 0xca0, v203
	v_lshlrev_b32_e32 v204, 1, v204
	v_lshl_add_u64 v[206:207], v[194:195], 0, v[204:205]
	global_load_dwordx4 v[208:211], v[198:199], off
	v_add_co_u32_e64 v194, s[98:99], s40, v206
	v_addc_co_u32_e64 v195, s[98:99], 0, v207, s[98:99]
	global_load_dwordx4 v[212:215], v[194:195], off offset:256
	v_add_co_u32_e64 v196, s[98:99], s41, v198
	v_addc_co_u32_e64 v197, s[98:99], 0, v199, s[98:99]
	global_load_dwordx4 v[216:219], v[196:197], off
	v_add_co_u32_e64 v200, s[98:99], s42, v206
	v_addc_co_u32_e64 v201, s[98:99], 0, v207, s[98:99]
	global_load_dwordx4 v[220:223], v[200:201], off offset:256
	v_add_co_u32_e64 v194, s[98:99], s43, v198
	v_addc_co_u32_e64 v195, s[98:99], 0, v199, s[98:99]
	global_load_dwordx4 v[114:117], v[194:195], off
	v_add_co_u32_e64 v196, s[98:99], s44, v206
	v_addc_co_u32_e64 v197, s[98:99], 0, v207, s[98:99]
	global_load_dwordx4 v[118:121], v[196:197], off offset:256
	v_add_co_u32_e64 v200, s[98:99], s45, v198
	v_addc_co_u32_e64 v201, s[98:99], 0, v199, s[98:99]
	global_load_dwordx4 v[122:125], v[200:201], off
	v_add_co_u32_e64 v202, s[98:99], s46, v206
	v_addc_co_u32_e64 v203, s[98:99], 0, v207, s[98:99]
	global_load_dwordx4 v[126:129], v[202:203], off offset:256
	s_waitcnt vmcnt(11)
	v_lshlrev_b32_e32 v18, 16, v2
	v_and_b32_e32 v19, 0xffff0000, v2
	v_lshlrev_b32_e32 v2, 16, v3
	v_and_b32_e32 v3, 0xffff0000, v3
	s_waitcnt vmcnt(8)
; template <int DQK, int DV, bool BIAS> ...
;     ...
; #pragma unroll
;     for (int ks = 0; ks < NKS; ++ks) qf[ks] = ks < 4 ? *(const bf16x8*)(Qw + (size_t)r32 * ldq + ks * 16 + hi * 8) : *(const bf16x8*)(Q2w + (size_t)r32 * ldq2 + (ks - 4) * 16 + hi * 8);
; #pragma unroll
;     for (int ks = 0; ks < 4; ++ks) qf[ks] = scale_frag(qf[ks], cs);
;     ...
;     u32x4 pw[4];
; #pragma unroll
;     for (int j = 0; j < TPB; ++j) { ATT_LOAD(j, j); ATT_STORE(j, j); }
; #pragma unroll
;     for (int j = 0; j < TPB; ++j) ATT_LOAD(TPB + j, j);
	v_lshlrev_b32_e32 v30, 16, v14
	v_and_b32_e32 v31, 0xffff0000, v14
	v_lshlrev_b32_e32 v32, 16, v16
	v_and_b32_e32 v33, 0xffff0000, v16
	v_lshlrev_b32_e32 v16, 16, v17
	v_pk_mul_f32 v[2:3], v[2:3], s[6:7] op_sel_hi:[1,0]
	v_and_b32_e32 v17, 0xffff0000, v17
	v_pk_mul_f32 v[30:31], v[30:31], s[6:7] op_sel_hi:[1,0]
	v_pk_mul_f32 v[32:33], v[32:33], s[6:7] op_sel_hi:[1,0]
	v_cvt_pk_bf16_f32 v99, v2, v3
	v_pk_mul_f32 v[2:3], v[16:17], s[6:7] op_sel_hi:[1,0]
	v_lshlrev_b32_e32 v20, 16, v4
	v_and_b32_e32 v21, 0xffff0000, v4
	v_pk_mul_f32 v[18:19], v[18:19], s[6:7] op_sel_hi:[1,0]
	v_cvt_pk_bf16_f32 v110, v30, v31
	v_cvt_pk_bf16_f32 v112, v32, v33
	v_cvt_pk_bf16_f32 v113, v2, v3
	v_ashrrev_i32_e32 v30, 3, v34
	v_mov_b64_e32 v[2:3], s[22:23]
	v_lshlrev_b32_e32 v32, 4, v34
	v_lshlrev_b32_e32 v4, 16, v5
	v_and_b32_e32 v5, 0xffff0000, v5
	v_pk_mul_f32 v[20:21], v[20:21], s[6:7] op_sel_hi:[1,0]
	v_cvt_pk_bf16_f32 v98, v18, v19
	v_mad_i64_i32 v[2:3], s[22:23], v30, s37, v[2:3]
	v_and_b32_e32 v18, 0x70, v32
	v_mov_b32_e32 v19, v131
	v_lshlrev_b32_e32 v22, 16, v6
	v_and_b32_e32 v23, 0xffff0000, v6
	v_pk_mul_f32 v[4:5], v[4:5], s[6:7] op_sel_hi:[1,0]
	v_cvt_pk_bf16_f32 v100, v20, v21
	v_lshl_add_u64 v[20:21], v[2:3], 0, v[18:19]
	v_and_b32_e32 v2, 0xffffffe0, v30
	v_pk_mul_f32 v[22:23], v[22:23], s[6:7] op_sel_hi:[1,0]
	v_cvt_pk_bf16_f32 v101, v4, v5
	v_ashrrev_i32_e32 v3, 31, v2
	v_lshlrev_b32_e32 v4, 3, v34
	v_cvt_pk_bf16_f32 v102, v22, v23
	v_lshlrev_b64 v[22:23], 1, v[2:3]
	v_and_b32_e32 v37, 24, v4
	v_bfe_u32 v33, v34, 2, 6
	v_lshl_add_u64 v[2:3], s[20:21], 0, v[22:23]
	v_lshlrev_b32_e32 v4, 1, v37
	v_mov_b32_e32 v5, v131
	v_lshlrev_b32_e32 v24, 16, v8
	v_and_b32_e32 v25, 0xffff0000, v8
	v_lshl_add_u64 v[2:3], v[2:3], 0, v[4:5]
	v_mul_u32_u24_e32 v4, 0xca0, v33
	v_lshlrev_b32_e32 v26, 16, v10
	v_and_b32_e32 v27, 0xffff0000, v10
	v_lshlrev_b32_e32 v10, 16, v11
	v_and_b32_e32 v11, 0xffff0000, v11
	v_pk_mul_f32 v[24:25], v[24:25], s[6:7] op_sel_hi:[1,0]
	v_lshlrev_b32_e32 v4, 1, v4
	v_pk_mul_f32 v[10:11], v[10:11], s[6:7] op_sel_hi:[1,0]
	v_cvt_pk_bf16_f32 v104, v24, v25
	v_lshl_add_u64 v[24:25], v[2:3], 0, v[4:5]
	v_cvt_pk_bf16_f32 v107, v10, v11
	v_add_co_u32_e32 v10, vcc, s40, v24
	v_pk_mul_f32 v[26:27], v[26:27], s[6:7] op_sel_hi:[1,0]
	s_nop 0
	v_addc_co_u32_e32 v11, vcc, 0, v25, vcc
	v_lshlrev_b32_e32 v28, 16, v12
	v_and_b32_e32 v29, 0xffff0000, v12
	v_cvt_pk_bf16_f32 v106, v26, v27
	v_add_co_u32_e32 v26, vcc, s41, v20
	v_lshlrev_b32_e32 v6, 16, v7
	v_and_b32_e32 v7, 0xffff0000, v7
	v_lshlrev_b32_e32 v8, 16, v9
	v_and_b32_e32 v9, 0xffff0000, v9
	v_lshlrev_b32_e32 v12, 16, v13
	v_and_b32_e32 v13, 0xffff0000, v13
	v_lshlrev_b32_e32 v14, 16, v15
	v_and_b32_e32 v15, 0xffff0000, v15
	v_pk_mul_f32 v[28:29], v[28:29], s[6:7] op_sel_hi:[1,0]
	v_addc_co_u32_e32 v27, vcc, 0, v21, vcc
	v_pk_mul_f32 v[6:7], v[6:7], s[6:7] op_sel_hi:[1,0]
	v_pk_mul_f32 v[8:9], v[8:9], s[6:7] op_sel_hi:[1,0]
	v_pk_mul_f32 v[12:13], v[12:13], s[6:7] op_sel_hi:[1,0]
	v_pk_mul_f32 v[14:15], v[14:15], s[6:7] op_sel_hi:[1,0]
	v_cvt_pk_bf16_f32 v108, v28, v29
	v_add_co_u32_e32 v28, vcc, s42, v24
	v_cvt_pk_bf16_f32 v103, v6, v7
	v_cvt_pk_bf16_f32 v105, v8, v9
	v_cvt_pk_bf16_f32 v109, v12, v13
	v_cvt_pk_bf16_f32 v111, v14, v15
	v_addc_co_u32_e32 v29, vcc, 0, v25, vcc
	s_nop 0
	v_add_co_u32_e32 v28, vcc, s44, v24
	v_mad_i64_i32 v[26:27], s[20:21], v30, s37, 0
	s_nop 0
	v_addc_co_u32_e32 v29, vcc, 0, v25, vcc
	v_add_co_u32_e32 v24, vcc, s46, v24
	v_mul_lo_u32 v38, v30, s39
	s_nop 0
	v_addc_co_u32_e32 v25, vcc, 0, v25, vcc
	v_add_co_u32_e32 v30, vcc, s43, v20
	v_and_b32_e32 v39, 0xfffff000, v32
	s_nop 0
	v_addc_co_u32_e32 v31, vcc, 0, v21, vcc
	v_add_co_u32_e32 v20, vcc, s45, v20
	v_and_b32_e32 v40, 0xfc0, v32
	s_nop 0
	v_addc_co_u32_e32 v21, vcc, 0, v21, vcc
	v_add_u32_e32 v20, 0, v38
	v_and_b32_e32 v41, 48, v32
	v_add3_u32 v21, 0, v39, v40
	v_add_u32_e32 v133, v20, v18
	v_add_u32_e32 v140, v21, v41
	s_waitcnt vmcnt(7)
	ds_write_b128 v133, v[208:211]
	s_waitcnt vmcnt(6)
	ds_write_b128 v140, v[212:215] offset:36864
	s_waitcnt vmcnt(5)
	ds_write_b128 v133, v[216:219] offset:9216
	s_waitcnt vmcnt(4)
	ds_write_b128 v140, v[220:223] offset:45056
	v_and_b32_e32 v2, 0xc0, v32
	v_lshlrev_b32_e32 v3, 1, v34
	v_add3_u32 v2, 0, v36, v2
	v_and_b32_e32 v3, 32, v3
	v_add3_u32 v141, v2, v3, v37
	v_mul_hi_u32_u24_e32 v3, 0x1940, v33
	v_mul_u32_u24_e32 v2, 0x1940, v33
	v_mad_i64_i32 v[2:3], s[20:21], s18, v139, v[2:3]
	v_and_b32_e32 v4, 3, v34
	v_lshl_or_b32 v2, v4, 4, v2
	v_lshl_add_u64 v[2:3], v[2:3], 0, v[22:23]
	v_lshl_add_u64 v[134:135], s[4:5], 0, v[2:3]
	v_mad_i64_i32 v[2:3], s[18:19], s18, v139, v[26:27]
	v_lshl_add_u64 v[2:3], v[2:3], 0, v[18:19]
	v_add_u32_e32 v142, 0x9000, v141
	v_lshl_add_u64 v[136:137], s[4:5], 0, v[2:3]
	v_mov_b32_e32 v18, v131
	v_mov_b32_e32 v20, v131
	v_mov_b32_e32 v21, v131
	v_mov_b32_e32 v22, v131
	v_mov_b32_e32 v23, v131
	v_mov_b32_e32 v24, v131
	v_mov_b32_e32 v25, v131
	v_mov_b32_e32 v26, v131
	v_mov_b32_e32 v27, v131
	v_mov_b32_e32 v28, v131
	v_mov_b32_e32 v29, v131
	v_mov_b32_e32 v30, v131
	v_mov_b32_e32 v31, v131
	v_mov_b32_e32 v32, v131
	v_mov_b32_e32 v33, v131
	v_mov_b32_e32 v2, v131
	v_mov_b32_e32 v3, v131
	v_mov_b32_e32 v4, v131
	v_mov_b32_e32 v5, v131
	v_mov_b32_e32 v6, v131
	v_mov_b32_e32 v7, v131
	v_mov_b32_e32 v8, v131
	v_mov_b32_e32 v9, v131
	v_mov_b32_e32 v10, v131
	v_mov_b32_e32 v11, v131
	v_mov_b32_e32 v12, v131
	v_mov_b32_e32 v13, v131
	v_mov_b32_e32 v14, v131
	v_mov_b32_e32 v15, v131
	v_mov_b32_e32 v16, v131
	v_mov_b32_e32 v17, v131
	s_mov_b64 s[18:19], 0
	s_mov_b32 s22, 0
	s_branch .LBB0_602

; template <int DQK, int DV, bool BIAS> ...
;     ...
;     const bf16_t* kptr = Kg + (size_t)(tid >> 3) * ldk + (tid & 7) * 8;
;     const bf16_t* k2ptr = (DQK == 96) ? K2g + (size_t)(tid >> 2) * ldk2 + (tid & 3) * 8 : nullptr;
;     ...
;     u32x4 pw[4];
; #pragma unroll
;     for (int j = 0; j < TPB; ++j) { ATT_LOAD(j, j); ATT_STORE(j, j); }
; #pragma unroll
;     for (int j = 0; j < TPB; ++j) ATT_LOAD(TPB + j, j);
; __device__ __forceinline__ void attn_phase(PPtr P, int li, LAS unsigned char* lds, int vcu, int wave, int lane) {
;     ...
;         attn_pass<96, 64, false>(lds, mlaq + qrow * 768 + h * 64, 768, mlaq + qrow * 768 + 512 + h * 32, 768, mlakv + seq0 * 1024 + h * 128, 1024, proj + seq0 * LDP + C_CKR, LDP,
;                                  mlakv + seq0 * 1024 + h * 128 + 64, 1024, qb * 256 + wave * 32, 0.10206207261596575f * LOG2E, 0.f, (const float*)(P->ws + OFF_ROPE), o);
.LBB0_620:
	s_or_b64 exec, exec, s[46:47]
	v_and_b32_e32 v14, 0xffffffe0, v22
	v_lshlrev_b32_e32 v8, 3, v26
	v_ashrrev_i32_e32 v15, 31, v14
	v_and_b32_e32 v29, 24, v8
	v_lshl_add_u64 v[6:7], v[14:15], 1, s[42:43]
	v_lshlrev_b32_e32 v8, 1, v29
	v_mov_b32_e32 v9, v149
	v_lshl_add_u64 v[6:7], v[6:7], 0, v[8:9]
	v_lshlrev_b32_e32 v8, 9, v26
	v_and_b32_e32 v16, 0x1f800, v8
	v_mov_b32_e32 v17, v149
	v_lshl_add_u64 v[24:25], v[6:7], 0, v[16:17]
	global_load_dwordx4 v[6:9], v[24:25], off offset:128
	v_add_co_u32_e32 v200, vcc, 0x20000, v18
	s_nop 1
	v_addc_co_u32_e32 v201, vcc, 0, v19, vcc
	global_load_dwordx4 v[192:195], v[200:201], off
	v_lshl_add_u64 v[202:203], v[24:25], 0, s[20:21]
	v_add_co_u32_e32 v200, vcc, 0x20000, v202
	s_nop 1
	v_addc_co_u32_e32 v201, vcc, 0, v203, vcc
	global_load_dwordx4 v[196:199], v[200:201], off
	s_and_saveexec_b64 s[98:99], s[6:7]
	v_add_co_u32_e32 v200, vcc, 0x65000, v20
	s_nop 1
	v_addc_co_u32_e32 v201, vcc, 0, v21, vcc
	global_load_dwordx4 v[126:129], v[200:201], off
	s_or_b64 exec, exec, s[98:99]
	v_mul_lo_u32 v22, v22, s58
	v_mul_lo_u32 v17, v13, s58
	v_add_u32_e32 v22, 0, v22
	v_add_u32_e32 v147, v22, v12
	v_add3_u32 v31, 0, v17, v152
	s_waitcnt vmcnt(4)
	ds_write_b128 v147, v[2:5]
	s_and_saveexec_b64 s[42:43], s[6:7]
	ds_write_b128 v31, v[122:125] offset:128
	s_or_b64 exec, exec, s[42:43]
	v_add_co_u32_e32 v2, vcc, 0x20000, v18
	v_lshlrev_b32_e32 v30, 4, v26
	s_nop 0
	v_addc_co_u32_e32 v3, vcc, 0, v19, vcc
	v_and_b32_e32 v22, 0xfffff000, v30
	v_add_u32_e32 v22, 0, v22
	v_and_b32_e32 v23, 0xfc0, v30
	v_and_b32_e32 v32, 48, v30
	v_add3_u32 v151, v22, v23, v32
	s_waitcnt vmcnt(3)
	ds_write_b128 v151, v[6:9] offset:53248
	s_and_saveexec_b64 s[42:43], s[6:7]
	s_cbranch_execz .LBB0_624
.LBB0_624:
	s_or_b64 exec, exec, s[42:43]
	v_lshl_add_u64 v[22:23], v[24:25], 0, s[20:21]
	v_add_co_u32_e32 v6, vcc, 0x20000, v22
	s_waitcnt vmcnt(0)
	ds_write_b128 v147, v[192:195] offset:13312
	v_addc_co_u32_e32 v7, vcc, 0, v23, vcc
	s_and_saveexec_b64 s[42:43], s[6:7]
	ds_write_b128 v31, v[126:129] offset:13440
	s_or_b64 exec, exec, s[42:43]
	v_add_co_u32_e32 v2, vcc, 0x40000, v18
	ds_write_b128 v151, v[196:199] offset:61440
	v_addc_co_u32_e32 v3, vcc, 0, v19, vcc
	global_load_dwordx4 v[130:133], v[2:3], off
	s_and_saveexec_b64 s[42:43], s[6:7]
	s_cbranch_execz .LBB0_628
	v_add_co_u32_e32 v2, vcc, 0xca000, v20
	s_nop 1
	v_addc_co_u32_e32 v3, vcc, 0, v21, vcc
	global_load_dwordx4 v[122:125], v[2:3], off
